# fix phase indexer-key LayerNorm + rope loop: first five trips unrolled, their row loads requested up front (one exposed memory latency instead of one per trip)
# baseline (speedup 1.0000x reference)
; __device__ __forceinline__ void phase_fix(KP kp, int l, unsigned char* shm) {
;     ...
;     const int li = tid & 15;
;     const f32x4 gg = *(const f32x4*)(kp->idx_g + l * 64 + li * 4), bb = *(const f32x4*)(kp->idx_b + l * 64 + li * 4);
;     for (int rb = bid * 32; rb < MT; rb += nb * 32) {
;       const int r = rb + (tid >> 4);
;       const bool samp = r >= MP;
;       const int sr = r - MP;
;       const int pos = samp ? 2048 + (sr & 31) : (r & 4095);
;       const f32x4 x = *(const f32x4*)((const float*)(ws + W_KIRAW) + (size_t)r * 64 + li * 4);
;       float s = x[0] + x[1] + x[2] + x[3];
;       s += __shfl_xor(s, 1); s += __shfl_xor(s, 2); s += __shfl_xor(s, 4); s += __shfl_xor(s, 8);
;       const float mean = s * (1.f / 64.f);
;       const f32x4 d = x - mean;
;       float ss = d[0] * d[0] + d[1] * d[1] + d[2] * d[2] + d[3] * d[3];
;       ss += __shfl_xor(ss, 1); ss += __shfl_xor(ss, 2); ss += __shfl_xor(ss, 4); ss += __shfl_xor(ss, 8);
;       const float rstd = rsqrtf(ss * (1.f / 64.f) + LN_EPS);
;       f32x4 y = d * rstd * gg + bb;
;       f32x4 pr;
; #pragma unroll
;       for (int e = 0; e < 4; ++e) pr[e] = __shfl_xor(y[e], 2);
;       if (li < 4) {
;         const int i0 = (li & 1) * 4;
;         const f32x4 t0 = *(const f32x4*)(rope + (size_t)pos * 16 + i0 * 2), t1 = *(const f32x4*)(rope + (size_t)pos * 16 + i0 * 2 + 4);
;         const float cc[4] = {t0[0], t0[2], t1[0], t1[2]}, sn[4] = {t0[1], t0[3], t1[1], t1[3]};
; #pragma unroll
;         for (int e = 0; e < 4; ++e) y[e] = (li < 2) ? (y[e] * cc[e] - pr[e] * sn[e]) : (pr[e] * sn[e] + y[e] * cc[e]);
;       }
.LBB0_2798:
	s_or_b64 exec, exec, s[0:1]
	v_readlane_b32 s0, v255, 14
	v_readlane_b32 s12, v254, 2
	v_readlane_b32 s1, v255, 15
	v_readlane_b32 s13, v254, 3
	v_mov_b32_e32 v27, v244
	s_xor_b64 s[0:1], s[0:1], -1
	s_waitcnt lgkmcnt(0)
	s_barrier
	s_load_dwordx2 s[14:15], s[12:13], 0xb0
	v_writelane_b32 v255, s0, 25
	v_and_b32_e32 v26, 15, v27
	s_nop 0
	v_writelane_b32 v255, s1, 26
	v_readlane_b32 s0, v254, 10
	v_readlane_b32 s1, v254, 11
	s_andn2_b64 vcc, exec, s[0:1]
	s_cbranch_vccnz .LBB0_2807
	s_load_dwordx4 s[0:3], s[12:13], 0x30
	v_readlane_b32 s4, v255, 20
	v_readlane_b32 s5, v255, 21
	v_readlane_b32 s22, v255, 22
	s_mov_b32 s11, s5
	s_lshl_b32 s10, s22, 6
	s_lshl_b64 s[4:5], s[10:11], 2
	s_waitcnt lgkmcnt(0)
	s_add_u32 s2, s2, s4
	s_addc_u32 s3, s3, s5
	v_lshlrev_b32_e32 v9, 4, v26
	s_add_u32 s0, s0, s4
	s_addc_u32 s1, s1, s5
	global_load_dwordx4 v[0:3], v9, s[2:3]
	global_load_dwordx4 v[4:7], v9, s[0:1]
	v_and_b32_e32 v11, 64, v252
	v_xor_b32_e32 v10, 1, v252
	v_add_u32_e32 v11, 64, v11
	v_cmp_lt_i32_e32 vcc, v10, v11
	v_ashrrev_i32_e32 v28, 4, v27
	v_and_b32_e32 v14, 31, v28
	v_cndmask_b32_e32 v10, v252, v10, vcc
	v_lshlrev_b32_e32 v30, 2, v10
	v_xor_b32_e32 v10, 2, v252
	v_cmp_lt_i32_e32 vcc, v10, v11
	s_mov_b64 s[0:1], 0x3980000
	s_movk_i32 s4, 0xe0
	v_cndmask_b32_e32 v10, v252, v10, vcc
	v_lshlrev_b32_e32 v31, 2, v10
	v_xor_b32_e32 v10, 4, v252
	v_cmp_lt_i32_e32 vcc, v10, v11
	s_mov_b32 s5, s11
	v_readlane_b32 s23, v255, 23
	v_cndmask_b32_e32 v10, v252, v10, vcc
	v_lshlrev_b32_e32 v32, 2, v10
	v_xor_b32_e32 v10, 8, v252
	v_cmp_lt_i32_e32 vcc, v10, v11
	s_add_u32 s6, s14, 0xbf80000
	v_lshlrev_b32_e32 v8, 2, v26
	v_cndmask_b32_e32 v10, v252, v10, vcc
	v_lshlrev_b32_e32 v33, 2, v10
	v_lshlrev_b32_e32 v10, 5, v27
	v_and_b32_e32 v16, 32, v10
	v_lshl_add_u64 v[10:11], s[14:15], 0, v[16:17]
	v_lshl_add_u64 v[12:13], v[10:11], 0, s[0:1]
	v_and_or_b32 v10, v9, 32, v14
	v_and_or_b32 v9, v9, s4, v14
	v_writelane_b32 v255, s4, 20
	s_addc_u32 s7, s15, 0
	s_add_u32 s8, s14, 0xbb80000
	v_writelane_b32 v255, s5, 21
	s_mov_b32 s4, s22
	v_and_b32_e32 v11, 4, v8
	s_mov_b32 s23, s11
	v_writelane_b32 v255, s4, 22
	v_or_b32_e32 v29, 0x800, v14
	s_addc_u32 s9, s15, 0
	v_lshlrev_b32_e32 v14, 1, v11
	v_writelane_b32 v255, s5, 23
	s_lshl_b64 s[4:5], s[22:23], 23
	v_readlane_b32 s23, v254, 12
	v_lshl_or_b32 v16, v9, 4, v14
	v_lshl_or_b32 v9, v10, 3, v11
	v_add_u32_e32 v10, s23, v28
	s_lshl_b32 s20, s22, 9
	v_ashrrev_i32_e32 v11, 31, v10
	s_add_u32 s21, s4, 0xc200000
	v_lshlrev_b64 v[18:19], 8, v[10:11]
	v_cmp_gt_u32_e64 s[0:1], 2, v26
	v_cmp_gt_u32_e64 s[2:3], 4, v26
	v_lshrrev_b32_e32 v34, 2, v26
	v_lshl_add_u64 v[14:15], s[14:15], 0, v[16:17]
	s_addc_u32 s22, s5, 0
	v_lshl_or_b32 v18, v26, 4, v18
	v_lshlrev_b32_e32 v35, 1, v9
	v_lshlrev_b32_e32 v20, 2, v8
	v_readlane_b32 s24, v255, 4
	v_readlane_b32 s25, v255, 5
	v_lshl_add_u64 v[220:221], s[6:7], 0, v[18:19]
	global_load_dwordx4 v[200:203], v[220:221], off
	v_lshl_add_u64 v[220:221], v[220:221], 0, s[24:25]
	global_load_dwordx4 v[204:207], v[220:221], off
	v_lshl_add_u64 v[220:221], v[220:221], 0, s[24:25]
	global_load_dwordx4 v[208:211], v[220:221], off
	v_lshl_add_u64 v[220:221], v[220:221], 0, s[24:25]
	global_load_dwordx4 v[212:215], v[220:221], off
	v_lshl_add_u64 v[220:221], v[220:221], 0, s[24:25]
	global_load_dwordx4 v[216:219], v[220:221], off
	s_mov_b32 s4, 0x800000
	s_mov_b32 s10, 0x8000
	s_waitcnt vmcnt(0)
	v_mov_b32_e32 v8, v200
	v_mov_b32_e32 v9, v201
	v_mov_b32_e32 v10, v202
	v_mov_b32_e32 v11, v203
	v_add_f32_e32 v16, v8, v9
	v_add_f32_e32 v16, v10, v16
	v_add_f32_e32 v16, v11, v16
	ds_bpermute_b32 v21, v30, v16
	s_waitcnt lgkmcnt(0)
	v_add_f32_e32 v16, v16, v21
	ds_bpermute_b32 v21, v31, v16
	s_waitcnt lgkmcnt(0)
	v_add_f32_e32 v16, v16, v21
	ds_bpermute_b32 v21, v32, v16
	s_waitcnt lgkmcnt(0)
	v_add_f32_e32 v16, v16, v21
	ds_bpermute_b32 v21, v33, v16
	s_waitcnt lgkmcnt(0)
	v_add_f32_e32 v16, v16, v21
	v_fmamk_f32 v9, v16, 0xbc800000, v9
	v_fmamk_f32 v8, v16, 0xbc800000, v8
	v_fmamk_f32 v11, v16, 0xbc800000, v11
	v_fmac_f32_e32 v10, 0xbc800000, v16
	v_pk_mul_f32 v[24:25], v[8:9], v[8:9]
	v_pk_mul_f32 v[22:23], v[10:11], v[10:11]
	v_add_f32_e32 v16, v24, v25
	v_add_f32_e32 v16, v22, v16
	v_add_f32_e32 v16, v23, v16
	ds_bpermute_b32 v21, v30, v16
	s_waitcnt lgkmcnt(0)
	v_add_f32_e32 v16, v16, v21
	ds_bpermute_b32 v21, v31, v16
	s_waitcnt lgkmcnt(0)
	v_add_f32_e32 v16, v16, v21
	ds_bpermute_b32 v21, v32, v16
	s_waitcnt lgkmcnt(0)
	v_add_f32_e32 v16, v16, v21
	ds_bpermute_b32 v21, v33, v16
	s_waitcnt lgkmcnt(0)
	v_add_f32_e32 v16, v16, v21
	v_fmamk_f32 v16, v16, 0x3c800000, v249
	v_mul_f32_e32 v21, 0x4b800000, v16
	v_cmp_gt_f32_e32 vcc, s4, v16
	s_movk_i32 s4, 0x7fff
	s_nop 0
	v_cndmask_b32_e32 v16, v16, v21, vcc
	v_rsq_f32_e32 v16, v16
	s_nop 0
	v_mul_f32_e32 v21, 0x45800000, v16
	v_cndmask_b32_e32 v16, v16, v21, vcc
	v_pk_mul_f32 v[8:9], v[8:9], v[16:17] op_sel_hi:[1,0]
	v_pk_mul_f32 v[10:11], v[10:11], v[16:17] op_sel_hi:[1,0]
	v_pk_fma_f32 v[8:9], v[4:5], v[8:9], v[0:1]
	v_pk_fma_f32 v[10:11], v[6:7], v[10:11], v[2:3]
	ds_bpermute_b32 v22, v31, v8
	ds_bpermute_b32 v23, v31, v9
	ds_bpermute_b32 v24, v31, v10
	ds_bpermute_b32 v25, v31, v11
	v_add_u32_e32 v21, s23, v28
	v_cmp_lt_i32_e64 s[4:5], s4, v21
	v_cmp_gt_i32_e32 vcc, s10, v21
	s_and_saveexec_b64 s[10:11], s[2:3]
	s_cbranch_execz .Lfixki0_a
	v_and_b32_e32 v16, 0xfff, v21
	v_cndmask_b32_e64 v16, v16, v29, s[4:5]
	v_lshlrev_b32_e32 v16, 6, v16
	v_lshl_add_u64 v[40:41], v[12:13], 0, v[16:17]
	global_load_dwordx4 v[36:39], v[40:41], off
	s_nop 0
	global_load_dwordx4 v[40:43], v[40:41], off offset:16
	s_waitcnt vmcnt(1)
	v_mov_b32_e32 v45, v38
	v_mov_b32_e32 v38, v37
	s_waitcnt vmcnt(0)
	v_mov_b32_e32 v37, v42
	v_mov_b32_e32 v42, v41
	s_waitcnt lgkmcnt(2)
	v_pk_mul_f32 v[22:23], v[38:39], v[22:23]
	s_waitcnt lgkmcnt(0)
	v_pk_mul_f32 v[24:25], v[42:43], v[24:25]
	v_mov_b32_e32 v44, v36
	v_mov_b32_e32 v36, v40
	v_cndmask_b32_e64 v23, v23, -v23, s[0:1]
	v_cndmask_b32_e64 v22, v22, -v22, s[0:1]
	v_cndmask_b32_e64 v25, v25, -v25, s[0:1]
	v_cndmask_b32_e64 v24, v24, -v24, s[0:1]
	v_pk_fma_f32 v[8:9], v[8:9], v[44:45], v[22:23]
	v_pk_fma_f32 v[10:11], v[10:11], v[36:37], v[24:25]

; __device__ __forceinline__ void phase_fix(KP kp, int l, unsigned char* shm) {
;     ...
;     for (int rb = bid * 32; rb < MT; rb += nb * 32) {
;       const int r = rb + (tid >> 4);
;       const bool samp = r >= MP;
;       const int sr = r - MP;
;       const int pos = samp ? 2048 + (sr & 31) : (r & 4095);
;       const f32x4 x = *(const f32x4*)((const float*)(ws + W_KIRAW) + (size_t)r * 64 + li * 4);
;       float s = x[0] + x[1] + x[2] + x[3];
;       s += __shfl_xor(s, 1); s += __shfl_xor(s, 2); s += __shfl_xor(s, 4); s += __shfl_xor(s, 8);
;       const float mean = s * (1.f / 64.f);
;       const f32x4 d = x - mean;
;       float ss = d[0] * d[0] + d[1] * d[1] + d[2] * d[2] + d[3] * d[3];
;       ss += __shfl_xor(ss, 1); ss += __shfl_xor(ss, 2); ss += __shfl_xor(ss, 4); ss += __shfl_xor(ss, 8);
;       const float rstd = rsqrtf(ss * (1.f / 64.f) + LN_EPS);
;       f32x4 y = d * rstd * gg + bb;
;       f32x4 pr;
; #pragma unroll
;       for (int e = 0; e < 4; ++e) pr[e] = __shfl_xor(y[e], 2);
;       if (li < 4) {
;         const int i0 = (li & 1) * 4;
;         const f32x4 t0 = *(const f32x4*)(rope + (size_t)pos * 16 + i0 * 2), t1 = *(const f32x4*)(rope + (size_t)pos * 16 + i0 * 2 + 4);
;         const float cc[4] = {t0[0], t0[2], t1[0], t1[2]}, sn[4] = {t0[1], t0[3], t1[1], t1[3]};
; #pragma unroll
;         for (int e = 0; e < 4; ++e) y[e] = (li < 2) ? (y[e] * cc[e] - pr[e] * sn[e]) : (pr[e] * sn[e] + y[e] * cc[e]);
;       }
.Lfixki0_t:
	s_or_b64 exec, exec, s[10:11]
	s_waitcnt lgkmcnt(0)
	v_readlane_b32 s4, v255, 2
	v_readlane_b32 s5, v255, 3
	s_add_i32 s23, s23, s4
	v_readlane_b32 s4, v255, 4
	v_readlane_b32 s5, v255, 5
	s_cmp_gt_i32 s23, 0x81ff
	s_nop 0
	v_lshl_add_u64 v[18:19], v[18:19], 0, s[4:5]
	s_cbranch_scc1 .LBB0_2807
	s_mov_b32 s4, 0x800000
	s_mov_b32 s10, 0x8000
	v_mov_b32_e32 v8, v204
	v_mov_b32_e32 v9, v205
	v_mov_b32_e32 v10, v206
	v_mov_b32_e32 v11, v207
	v_add_f32_e32 v16, v8, v9
	v_add_f32_e32 v16, v10, v16
	v_add_f32_e32 v16, v11, v16
	ds_bpermute_b32 v21, v30, v16
	s_waitcnt lgkmcnt(0)
	v_add_f32_e32 v16, v16, v21
	ds_bpermute_b32 v21, v31, v16
	s_waitcnt lgkmcnt(0)
	v_add_f32_e32 v16, v16, v21
	ds_bpermute_b32 v21, v32, v16
	s_waitcnt lgkmcnt(0)
	v_add_f32_e32 v16, v16, v21
	ds_bpermute_b32 v21, v33, v16
	s_waitcnt lgkmcnt(0)
	v_add_f32_e32 v16, v16, v21
	v_fmamk_f32 v9, v16, 0xbc800000, v9
	v_fmamk_f32 v8, v16, 0xbc800000, v8
	v_fmamk_f32 v11, v16, 0xbc800000, v11
	v_fmac_f32_e32 v10, 0xbc800000, v16
	v_pk_mul_f32 v[24:25], v[8:9], v[8:9]
	v_pk_mul_f32 v[22:23], v[10:11], v[10:11]
	v_add_f32_e32 v16, v24, v25
	v_add_f32_e32 v16, v22, v16
	v_add_f32_e32 v16, v23, v16
	ds_bpermute_b32 v21, v30, v16
	s_waitcnt lgkmcnt(0)
	v_add_f32_e32 v16, v16, v21
	ds_bpermute_b32 v21, v31, v16
	s_waitcnt lgkmcnt(0)
	v_add_f32_e32 v16, v16, v21
	ds_bpermute_b32 v21, v32, v16
	s_waitcnt lgkmcnt(0)
	v_add_f32_e32 v16, v16, v21
	ds_bpermute_b32 v21, v33, v16
	s_waitcnt lgkmcnt(0)
	v_add_f32_e32 v16, v16, v21
	v_fmamk_f32 v16, v16, 0x3c800000, v249
	v_mul_f32_e32 v21, 0x4b800000, v16
	v_cmp_gt_f32_e32 vcc, s4, v16
	s_movk_i32 s4, 0x7fff
	s_nop 0
	v_cndmask_b32_e32 v16, v16, v21, vcc
	v_rsq_f32_e32 v16, v16
	s_nop 0
	v_mul_f32_e32 v21, 0x45800000, v16
	v_cndmask_b32_e32 v16, v16, v21, vcc
	v_pk_mul_f32 v[8:9], v[8:9], v[16:17] op_sel_hi:[1,0]
	v_pk_mul_f32 v[10:11], v[10:11], v[16:17] op_sel_hi:[1,0]
	v_pk_fma_f32 v[8:9], v[4:5], v[8:9], v[0:1]
	v_pk_fma_f32 v[10:11], v[6:7], v[10:11], v[2:3]
	ds_bpermute_b32 v22, v31, v8
	ds_bpermute_b32 v23, v31, v9
	ds_bpermute_b32 v24, v31, v10
	ds_bpermute_b32 v25, v31, v11
	v_add_u32_e32 v21, s23, v28
	v_cmp_lt_i32_e64 s[4:5], s4, v21
	v_cmp_gt_i32_e32 vcc, s10, v21
	s_and_saveexec_b64 s[10:11], s[2:3]
	s_cbranch_execz .Lfixki1_a
	v_and_b32_e32 v16, 0xfff, v21
	v_cndmask_b32_e64 v16, v16, v29, s[4:5]
	v_lshlrev_b32_e32 v16, 6, v16
	v_lshl_add_u64 v[40:41], v[12:13], 0, v[16:17]
	global_load_dwordx4 v[36:39], v[40:41], off
	s_nop 0
	global_load_dwordx4 v[40:43], v[40:41], off offset:16
	s_waitcnt vmcnt(1)
	v_mov_b32_e32 v45, v38
	v_mov_b32_e32 v38, v37
	s_waitcnt vmcnt(0)
	v_mov_b32_e32 v37, v42
	v_mov_b32_e32 v42, v41
	s_waitcnt lgkmcnt(2)
	v_pk_mul_f32 v[22:23], v[38:39], v[22:23]
	s_waitcnt lgkmcnt(0)
	v_pk_mul_f32 v[24:25], v[42:43], v[24:25]
	v_mov_b32_e32 v44, v36
	v_mov_b32_e32 v36, v40
	v_cndmask_b32_e64 v23, v23, -v23, s[0:1]
	v_cndmask_b32_e64 v22, v22, -v22, s[0:1]
	v_cndmask_b32_e64 v25, v25, -v25, s[0:1]
	v_cndmask_b32_e64 v24, v24, -v24, s[0:1]
	v_pk_fma_f32 v[8:9], v[8:9], v[44:45], v[22:23]
	v_pk_fma_f32 v[10:11], v[10:11], v[36:37], v[24:25]

; __device__ __forceinline__ void phase_fix(KP kp, int l, unsigned char* shm) {
;     ...
;     for (int rb = bid * 32; rb < MT; rb += nb * 32) {
;       const int r = rb + (tid >> 4);
;       const bool samp = r >= MP;
;       const int sr = r - MP;
;       const int pos = samp ? 2048 + (sr & 31) : (r & 4095);
;       const f32x4 x = *(const f32x4*)((const float*)(ws + W_KIRAW) + (size_t)r * 64 + li * 4);
;       float s = x[0] + x[1] + x[2] + x[3];
;       s += __shfl_xor(s, 1); s += __shfl_xor(s, 2); s += __shfl_xor(s, 4); s += __shfl_xor(s, 8);
;       const float mean = s * (1.f / 64.f);
;       const f32x4 d = x - mean;
;       float ss = d[0] * d[0] + d[1] * d[1] + d[2] * d[2] + d[3] * d[3];
;       ss += __shfl_xor(ss, 1); ss += __shfl_xor(ss, 2); ss += __shfl_xor(ss, 4); ss += __shfl_xor(ss, 8);
;       const float rstd = rsqrtf(ss * (1.f / 64.f) + LN_EPS);
;       f32x4 y = d * rstd * gg + bb;
;       f32x4 pr;
; #pragma unroll
;       for (int e = 0; e < 4; ++e) pr[e] = __shfl_xor(y[e], 2);
;       if (li < 4) {
;         const int i0 = (li & 1) * 4;
;         const f32x4 t0 = *(const f32x4*)(rope + (size_t)pos * 16 + i0 * 2), t1 = *(const f32x4*)(rope + (size_t)pos * 16 + i0 * 2 + 4);
;         const float cc[4] = {t0[0], t0[2], t1[0], t1[2]}, sn[4] = {t0[1], t0[3], t1[1], t1[3]};
; #pragma unroll
;         for (int e = 0; e < 4; ++e) y[e] = (li < 2) ? (y[e] * cc[e] - pr[e] * sn[e]) : (pr[e] * sn[e] + y[e] * cc[e]);
;       }
.Lfixki1_t:
	s_or_b64 exec, exec, s[10:11]
	s_waitcnt lgkmcnt(0)
	v_readlane_b32 s4, v255, 2
	v_readlane_b32 s5, v255, 3
	s_add_i32 s23, s23, s4
	v_readlane_b32 s4, v255, 4
	v_readlane_b32 s5, v255, 5
	s_cmp_gt_i32 s23, 0x81ff
	s_nop 0
	v_lshl_add_u64 v[18:19], v[18:19], 0, s[4:5]
	s_cbranch_scc1 .LBB0_2807
	s_mov_b32 s4, 0x800000
	s_mov_b32 s10, 0x8000
	v_mov_b32_e32 v8, v208
	v_mov_b32_e32 v9, v209
	v_mov_b32_e32 v10, v210
	v_mov_b32_e32 v11, v211
	v_add_f32_e32 v16, v8, v9
	v_add_f32_e32 v16, v10, v16
	v_add_f32_e32 v16, v11, v16
	ds_bpermute_b32 v21, v30, v16
	s_waitcnt lgkmcnt(0)
	v_add_f32_e32 v16, v16, v21
	ds_bpermute_b32 v21, v31, v16
	s_waitcnt lgkmcnt(0)
	v_add_f32_e32 v16, v16, v21
	ds_bpermute_b32 v21, v32, v16
	s_waitcnt lgkmcnt(0)
	v_add_f32_e32 v16, v16, v21
	ds_bpermute_b32 v21, v33, v16
	s_waitcnt lgkmcnt(0)
	v_add_f32_e32 v16, v16, v21
	v_fmamk_f32 v9, v16, 0xbc800000, v9
	v_fmamk_f32 v8, v16, 0xbc800000, v8
	v_fmamk_f32 v11, v16, 0xbc800000, v11
	v_fmac_f32_e32 v10, 0xbc800000, v16
	v_pk_mul_f32 v[24:25], v[8:9], v[8:9]
	v_pk_mul_f32 v[22:23], v[10:11], v[10:11]
	v_add_f32_e32 v16, v24, v25
	v_add_f32_e32 v16, v22, v16
	v_add_f32_e32 v16, v23, v16
	ds_bpermute_b32 v21, v30, v16
	s_waitcnt lgkmcnt(0)
	v_add_f32_e32 v16, v16, v21
	ds_bpermute_b32 v21, v31, v16
	s_waitcnt lgkmcnt(0)
	v_add_f32_e32 v16, v16, v21
	ds_bpermute_b32 v21, v32, v16
	s_waitcnt lgkmcnt(0)
	v_add_f32_e32 v16, v16, v21
	ds_bpermute_b32 v21, v33, v16
	s_waitcnt lgkmcnt(0)
	v_add_f32_e32 v16, v16, v21
	v_fmamk_f32 v16, v16, 0x3c800000, v249
	v_mul_f32_e32 v21, 0x4b800000, v16
	v_cmp_gt_f32_e32 vcc, s4, v16
	s_movk_i32 s4, 0x7fff
	s_nop 0
	v_cndmask_b32_e32 v16, v16, v21, vcc
	v_rsq_f32_e32 v16, v16
	s_nop 0
	v_mul_f32_e32 v21, 0x45800000, v16
	v_cndmask_b32_e32 v16, v16, v21, vcc
	v_pk_mul_f32 v[8:9], v[8:9], v[16:17] op_sel_hi:[1,0]
	v_pk_mul_f32 v[10:11], v[10:11], v[16:17] op_sel_hi:[1,0]
	v_pk_fma_f32 v[8:9], v[4:5], v[8:9], v[0:1]
	v_pk_fma_f32 v[10:11], v[6:7], v[10:11], v[2:3]
	ds_bpermute_b32 v22, v31, v8
	ds_bpermute_b32 v23, v31, v9
	ds_bpermute_b32 v24, v31, v10
	ds_bpermute_b32 v25, v31, v11
	v_add_u32_e32 v21, s23, v28
	v_cmp_lt_i32_e64 s[4:5], s4, v21
	v_cmp_gt_i32_e32 vcc, s10, v21
	s_and_saveexec_b64 s[10:11], s[2:3]
	s_cbranch_execz .Lfixki2_a
	v_and_b32_e32 v16, 0xfff, v21
	v_cndmask_b32_e64 v16, v16, v29, s[4:5]
	v_lshlrev_b32_e32 v16, 6, v16
	v_lshl_add_u64 v[40:41], v[12:13], 0, v[16:17]
	global_load_dwordx4 v[36:39], v[40:41], off
	s_nop 0
	global_load_dwordx4 v[40:43], v[40:41], off offset:16
	s_waitcnt vmcnt(1)
	v_mov_b32_e32 v45, v38
	v_mov_b32_e32 v38, v37
	s_waitcnt vmcnt(0)
	v_mov_b32_e32 v37, v42
	v_mov_b32_e32 v42, v41
	s_waitcnt lgkmcnt(2)
	v_pk_mul_f32 v[22:23], v[38:39], v[22:23]
	s_waitcnt lgkmcnt(0)
	v_pk_mul_f32 v[24:25], v[42:43], v[24:25]
	v_mov_b32_e32 v44, v36
	v_mov_b32_e32 v36, v40
	v_cndmask_b32_e64 v23, v23, -v23, s[0:1]
	v_cndmask_b32_e64 v22, v22, -v22, s[0:1]
	v_cndmask_b32_e64 v25, v25, -v25, s[0:1]
	v_cndmask_b32_e64 v24, v24, -v24, s[0:1]
	v_pk_fma_f32 v[8:9], v[8:9], v[44:45], v[22:23]
	v_pk_fma_f32 v[10:11], v[10:11], v[36:37], v[24:25]

; __device__ __forceinline__ void phase_fix(KP kp, int l, unsigned char* shm) {
;     ...
;     for (int rb = bid * 32; rb < MT; rb += nb * 32) {
;       const int r = rb + (tid >> 4);
;       const bool samp = r >= MP;
;       const int sr = r - MP;
;       const int pos = samp ? 2048 + (sr & 31) : (r & 4095);
;       const f32x4 x = *(const f32x4*)((const float*)(ws + W_KIRAW) + (size_t)r * 64 + li * 4);
;       float s = x[0] + x[1] + x[2] + x[3];
;       s += __shfl_xor(s, 1); s += __shfl_xor(s, 2); s += __shfl_xor(s, 4); s += __shfl_xor(s, 8);
;       const float mean = s * (1.f / 64.f);
;       const f32x4 d = x - mean;
;       float ss = d[0] * d[0] + d[1] * d[1] + d[2] * d[2] + d[3] * d[3];
;       ss += __shfl_xor(ss, 1); ss += __shfl_xor(ss, 2); ss += __shfl_xor(ss, 4); ss += __shfl_xor(ss, 8);
;       const float rstd = rsqrtf(ss * (1.f / 64.f) + LN_EPS);
;       f32x4 y = d * rstd * gg + bb;
;       f32x4 pr;
; #pragma unroll
;       for (int e = 0; e < 4; ++e) pr[e] = __shfl_xor(y[e], 2);
;       if (li < 4) {
;         const int i0 = (li & 1) * 4;
;         const f32x4 t0 = *(const f32x4*)(rope + (size_t)pos * 16 + i0 * 2), t1 = *(const f32x4*)(rope + (size_t)pos * 16 + i0 * 2 + 4);
;         const float cc[4] = {t0[0], t0[2], t1[0], t1[2]}, sn[4] = {t0[1], t0[3], t1[1], t1[3]};
; #pragma unroll
;         for (int e = 0; e < 4; ++e) y[e] = (li < 2) ? (y[e] * cc[e] - pr[e] * sn[e]) : (pr[e] * sn[e] + y[e] * cc[e]);
;       }
.Lfixki2_t:
	s_or_b64 exec, exec, s[10:11]
	s_waitcnt lgkmcnt(0)
	v_readlane_b32 s4, v255, 2
	v_readlane_b32 s5, v255, 3
	s_add_i32 s23, s23, s4
	v_readlane_b32 s4, v255, 4
	v_readlane_b32 s5, v255, 5
	s_cmp_gt_i32 s23, 0x81ff
	s_nop 0
	v_lshl_add_u64 v[18:19], v[18:19], 0, s[4:5]
	s_cbranch_scc1 .LBB0_2807
	s_mov_b32 s4, 0x800000
	s_mov_b32 s10, 0x8000
	v_mov_b32_e32 v8, v212
	v_mov_b32_e32 v9, v213
	v_mov_b32_e32 v10, v214
	v_mov_b32_e32 v11, v215
	v_add_f32_e32 v16, v8, v9
	v_add_f32_e32 v16, v10, v16
	v_add_f32_e32 v16, v11, v16
	ds_bpermute_b32 v21, v30, v16
	s_waitcnt lgkmcnt(0)
	v_add_f32_e32 v16, v16, v21
	ds_bpermute_b32 v21, v31, v16
	s_waitcnt lgkmcnt(0)
	v_add_f32_e32 v16, v16, v21
	ds_bpermute_b32 v21, v32, v16
	s_waitcnt lgkmcnt(0)
	v_add_f32_e32 v16, v16, v21
	ds_bpermute_b32 v21, v33, v16
	s_waitcnt lgkmcnt(0)
	v_add_f32_e32 v16, v16, v21
	v_fmamk_f32 v9, v16, 0xbc800000, v9
	v_fmamk_f32 v8, v16, 0xbc800000, v8
	v_fmamk_f32 v11, v16, 0xbc800000, v11
	v_fmac_f32_e32 v10, 0xbc800000, v16
	v_pk_mul_f32 v[24:25], v[8:9], v[8:9]
	v_pk_mul_f32 v[22:23], v[10:11], v[10:11]
	v_add_f32_e32 v16, v24, v25
	v_add_f32_e32 v16, v22, v16
	v_add_f32_e32 v16, v23, v16
	ds_bpermute_b32 v21, v30, v16
	s_waitcnt lgkmcnt(0)
	v_add_f32_e32 v16, v16, v21
	ds_bpermute_b32 v21, v31, v16
	s_waitcnt lgkmcnt(0)
	v_add_f32_e32 v16, v16, v21
	ds_bpermute_b32 v21, v32, v16
	s_waitcnt lgkmcnt(0)
	v_add_f32_e32 v16, v16, v21
	ds_bpermute_b32 v21, v33, v16
	s_waitcnt lgkmcnt(0)
	v_add_f32_e32 v16, v16, v21
	v_fmamk_f32 v16, v16, 0x3c800000, v249
	v_mul_f32_e32 v21, 0x4b800000, v16
	v_cmp_gt_f32_e32 vcc, s4, v16
	s_movk_i32 s4, 0x7fff
	s_nop 0
	v_cndmask_b32_e32 v16, v16, v21, vcc
	v_rsq_f32_e32 v16, v16
	s_nop 0
	v_mul_f32_e32 v21, 0x45800000, v16
	v_cndmask_b32_e32 v16, v16, v21, vcc
	v_pk_mul_f32 v[8:9], v[8:9], v[16:17] op_sel_hi:[1,0]
	v_pk_mul_f32 v[10:11], v[10:11], v[16:17] op_sel_hi:[1,0]
	v_pk_fma_f32 v[8:9], v[4:5], v[8:9], v[0:1]
	v_pk_fma_f32 v[10:11], v[6:7], v[10:11], v[2:3]
	ds_bpermute_b32 v22, v31, v8
	ds_bpermute_b32 v23, v31, v9
	ds_bpermute_b32 v24, v31, v10
	ds_bpermute_b32 v25, v31, v11
	v_add_u32_e32 v21, s23, v28
	v_cmp_lt_i32_e64 s[4:5], s4, v21
	v_cmp_gt_i32_e32 vcc, s10, v21
	s_and_saveexec_b64 s[10:11], s[2:3]
	s_cbranch_execz .Lfixki3_a
	v_and_b32_e32 v16, 0xfff, v21
	v_cndmask_b32_e64 v16, v16, v29, s[4:5]
	v_lshlrev_b32_e32 v16, 6, v16
	v_lshl_add_u64 v[40:41], v[12:13], 0, v[16:17]
	global_load_dwordx4 v[36:39], v[40:41], off
	s_nop 0
	global_load_dwordx4 v[40:43], v[40:41], off offset:16
	s_waitcnt vmcnt(1)
	v_mov_b32_e32 v45, v38
	v_mov_b32_e32 v38, v37
	s_waitcnt vmcnt(0)
	v_mov_b32_e32 v37, v42
	v_mov_b32_e32 v42, v41
	s_waitcnt lgkmcnt(2)
	v_pk_mul_f32 v[22:23], v[38:39], v[22:23]
	s_waitcnt lgkmcnt(0)
	v_pk_mul_f32 v[24:25], v[42:43], v[24:25]
	v_mov_b32_e32 v44, v36
	v_mov_b32_e32 v36, v40
	v_cndmask_b32_e64 v23, v23, -v23, s[0:1]
	v_cndmask_b32_e64 v22, v22, -v22, s[0:1]
	v_cndmask_b32_e64 v25, v25, -v25, s[0:1]
	v_cndmask_b32_e64 v24, v24, -v24, s[0:1]
	v_pk_fma_f32 v[8:9], v[8:9], v[44:45], v[22:23]
	v_pk_fma_f32 v[10:11], v[10:11], v[36:37], v[24:25]

; __device__ __forceinline__ void phase_fix(KP kp, int l, unsigned char* shm) {
;     ...
;     for (int rb = bid * 32; rb < MT; rb += nb * 32) {
;       const int r = rb + (tid >> 4);
;       const bool samp = r >= MP;
;       const int sr = r - MP;
;       const int pos = samp ? 2048 + (sr & 31) : (r & 4095);
;       const f32x4 x = *(const f32x4*)((const float*)(ws + W_KIRAW) + (size_t)r * 64 + li * 4);
;       float s = x[0] + x[1] + x[2] + x[3];
;       s += __shfl_xor(s, 1); s += __shfl_xor(s, 2); s += __shfl_xor(s, 4); s += __shfl_xor(s, 8);
;       const float mean = s * (1.f / 64.f);
;       const f32x4 d = x - mean;
;       float ss = d[0] * d[0] + d[1] * d[1] + d[2] * d[2] + d[3] * d[3];
;       ss += __shfl_xor(ss, 1); ss += __shfl_xor(ss, 2); ss += __shfl_xor(ss, 4); ss += __shfl_xor(ss, 8);
;       const float rstd = rsqrtf(ss * (1.f / 64.f) + LN_EPS);
;       f32x4 y = d * rstd * gg + bb;
;       f32x4 pr;
; #pragma unroll
;       for (int e = 0; e < 4; ++e) pr[e] = __shfl_xor(y[e], 2);
;       if (li < 4) {
;         const int i0 = (li & 1) * 4;
;         const f32x4 t0 = *(const f32x4*)(rope + (size_t)pos * 16 + i0 * 2), t1 = *(const f32x4*)(rope + (size_t)pos * 16 + i0 * 2 + 4);
;         const float cc[4] = {t0[0], t0[2], t1[0], t1[2]}, sn[4] = {t0[1], t0[3], t1[1], t1[3]};
; #pragma unroll
;         for (int e = 0; e < 4; ++e) y[e] = (li < 2) ? (y[e] * cc[e] - pr[e] * sn[e]) : (pr[e] * sn[e] + y[e] * cc[e]);
;       }
.Lfixki3_t:
	s_or_b64 exec, exec, s[10:11]
	s_waitcnt lgkmcnt(0)
	v_readlane_b32 s4, v255, 2
	v_readlane_b32 s5, v255, 3
	s_add_i32 s23, s23, s4
	v_readlane_b32 s4, v255, 4
	v_readlane_b32 s5, v255, 5
	s_cmp_gt_i32 s23, 0x81ff
	s_nop 0
	v_lshl_add_u64 v[18:19], v[18:19], 0, s[4:5]
	s_cbranch_scc1 .LBB0_2807
	s_mov_b32 s4, 0x800000
	s_mov_b32 s10, 0x8000
	v_mov_b32_e32 v8, v216
	v_mov_b32_e32 v9, v217
	v_mov_b32_e32 v10, v218
	v_mov_b32_e32 v11, v219
	v_add_f32_e32 v16, v8, v9
	v_add_f32_e32 v16, v10, v16
	v_add_f32_e32 v16, v11, v16
	ds_bpermute_b32 v21, v30, v16
	s_waitcnt lgkmcnt(0)
	v_add_f32_e32 v16, v16, v21
	ds_bpermute_b32 v21, v31, v16
	s_waitcnt lgkmcnt(0)
	v_add_f32_e32 v16, v16, v21
	ds_bpermute_b32 v21, v32, v16
	s_waitcnt lgkmcnt(0)
	v_add_f32_e32 v16, v16, v21
	ds_bpermute_b32 v21, v33, v16
	s_waitcnt lgkmcnt(0)
	v_add_f32_e32 v16, v16, v21
	v_fmamk_f32 v9, v16, 0xbc800000, v9
	v_fmamk_f32 v8, v16, 0xbc800000, v8
	v_fmamk_f32 v11, v16, 0xbc800000, v11
	v_fmac_f32_e32 v10, 0xbc800000, v16
	v_pk_mul_f32 v[24:25], v[8:9], v[8:9]
	v_pk_mul_f32 v[22:23], v[10:11], v[10:11]
	v_add_f32_e32 v16, v24, v25
	v_add_f32_e32 v16, v22, v16
	v_add_f32_e32 v16, v23, v16
	ds_bpermute_b32 v21, v30, v16
	s_waitcnt lgkmcnt(0)
	v_add_f32_e32 v16, v16, v21
	ds_bpermute_b32 v21, v31, v16
	s_waitcnt lgkmcnt(0)
	v_add_f32_e32 v16, v16, v21
	ds_bpermute_b32 v21, v32, v16
	s_waitcnt lgkmcnt(0)
	v_add_f32_e32 v16, v16, v21
	ds_bpermute_b32 v21, v33, v16
	s_waitcnt lgkmcnt(0)
	v_add_f32_e32 v16, v16, v21
	v_fmamk_f32 v16, v16, 0x3c800000, v249
	v_mul_f32_e32 v21, 0x4b800000, v16
	v_cmp_gt_f32_e32 vcc, s4, v16
	s_movk_i32 s4, 0x7fff
	s_nop 0
	v_cndmask_b32_e32 v16, v16, v21, vcc
	v_rsq_f32_e32 v16, v16
	s_nop 0
	v_mul_f32_e32 v21, 0x45800000, v16
	v_cndmask_b32_e32 v16, v16, v21, vcc
	v_pk_mul_f32 v[8:9], v[8:9], v[16:17] op_sel_hi:[1,0]
	v_pk_mul_f32 v[10:11], v[10:11], v[16:17] op_sel_hi:[1,0]
	v_pk_fma_f32 v[8:9], v[4:5], v[8:9], v[0:1]
	v_pk_fma_f32 v[10:11], v[6:7], v[10:11], v[2:3]
	ds_bpermute_b32 v22, v31, v8
	ds_bpermute_b32 v23, v31, v9
	ds_bpermute_b32 v24, v31, v10
	ds_bpermute_b32 v25, v31, v11
	v_add_u32_e32 v21, s23, v28
	v_cmp_lt_i32_e64 s[4:5], s4, v21
	v_cmp_gt_i32_e32 vcc, s10, v21
	s_and_saveexec_b64 s[10:11], s[2:3]
	s_cbranch_execz .Lfixki4_a
	v_and_b32_e32 v16, 0xfff, v21
	v_cndmask_b32_e64 v16, v16, v29, s[4:5]
	v_lshlrev_b32_e32 v16, 6, v16
	v_lshl_add_u64 v[40:41], v[12:13], 0, v[16:17]
	global_load_dwordx4 v[36:39], v[40:41], off
	s_nop 0
	global_load_dwordx4 v[40:43], v[40:41], off offset:16
	s_waitcnt vmcnt(1)
	v_mov_b32_e32 v45, v38
	v_mov_b32_e32 v38, v37
	s_waitcnt vmcnt(0)
	v_mov_b32_e32 v37, v42
	v_mov_b32_e32 v42, v41
	s_waitcnt lgkmcnt(2)
	v_pk_mul_f32 v[22:23], v[38:39], v[22:23]
	s_waitcnt lgkmcnt(0)
	v_pk_mul_f32 v[24:25], v[42:43], v[24:25]
	v_mov_b32_e32 v44, v36
	v_mov_b32_e32 v36, v40
	v_cndmask_b32_e64 v23, v23, -v23, s[0:1]
	v_cndmask_b32_e64 v22, v22, -v22, s[0:1]
	v_cndmask_b32_e64 v25, v25, -v25, s[0:1]
	v_cndmask_b32_e64 v24, v24, -v24, s[0:1]
	v_pk_fma_f32 v[8:9], v[8:9], v[44:45], v[22:23]
	v_pk_fma_f32 v[10:11], v[10:11], v[36:37], v[24:25]

; __device__ __forceinline__ void phase_fix(KP kp, int l, unsigned char* shm) {
;     ...
;     for (int rb = bid * 32; rb < MT; rb += nb * 32) {
.Lfixki4_t:
	s_or_b64 exec, exec, s[10:11]
	s_waitcnt lgkmcnt(0)
	v_readlane_b32 s4, v255, 2
	v_readlane_b32 s5, v255, 3
	s_add_i32 s23, s23, s4
	v_readlane_b32 s4, v255, 4
	v_readlane_b32 s5, v255, 5
	s_cmp_gt_i32 s23, 0x81ff
	s_nop 0
	v_lshl_add_u64 v[18:19], v[18:19], 0, s[4:5]
	s_cbranch_scc1 .LBB0_2807
	s_branch .LBB0_2801
